# attention units: waves 4-7 start the key-block loop ~640 cycles after waves 0-3 (stagger of the two SIMD partners)
# baseline (speedup 1.0000x reference)
.LBB0_540:
	s_or_b64 exec, exec, s[4:5]
	v_mul_lo_u32 v52, v58, s45
	v_add3_u32 v52, 0, v52, v50
	s_waitcnt vmcnt(0)
	ds_write_b128 v52, v[2:5]
	v_mul_lo_u32 v2, v59, s45
	v_mul_lo_u32 v3, v60, s45
	v_add3_u32 v2, 0, v2, v50
	v_add3_u32 v3, 0, v3, v50
	ds_write_b128 v2, v[10:13]
	ds_write_b128 v3, v[6:9]
	v_mul_lo_u32 v4, v61, s45
	v_mul_lo_u32 v5, v62, s45
	v_mul_lo_u32 v6, v63, s45
	v_add3_u32 v4, 0, v4, v50
	v_add3_u32 v5, 0, v5, v50
	v_add3_u32 v6, 0, v6, v50
	ds_write_b128 v4, v[18:21]
	ds_write_b128 v5, v[14:17]
	ds_write_b128 v6, v[26:29]
	ds_write_b128 v52, v[22:25] offset:55296
	ds_write_b128 v2, v[34:37] offset:55296
	ds_write_b128 v3, v[30:33] offset:55296
	ds_write_b128 v4, v[42:45] offset:55296
	ds_write_b128 v5, v[38:41] offset:55296
	ds_write_b128 v6, v[46:49] offset:55296
	v_lshlrev_b32_e32 v2, 6, v55
	v_or_b32_e32 v3, v2, v191
	v_add_u32_e32 v186, 0, v0
	v_mad_u32_u24 v4, v3, s45, v186
	v_bfe_u32 v51, v56, 2, 2
	s_waitcnt lgkmcnt(0)
	s_barrier
	s_cmpk_lt_u32 s92, 0x100
	s_cbranch_scc1 .Lattn_nostag
	s_sleep 10
.Lattn_nostag:
	ds_read_b128 v[160:163], v4
	ds_read_b128 v[156:159], v4 offset:32
	ds_read_b128 v[152:155], v4 offset:64
	ds_read_b128 v[148:151], v4 offset:96
	v_lshlrev_b32_e32 v4, 2, v54
	v_lshlrev_b32_e32 v6, 1, v56
	v_or_b32_e32 v194, v4, v51
	v_and_b32_e32 v6, 32, v6
	v_and_b32_e32 v7, 24, v64
	v_or_b32_e32 v5, v194, v2
	v_add3_u32 v188, 0, v6, v7
	v_mad_u32_u24 v5, v5, s45, v188
	ds_read_b64_tr_b16 v[136:137], v5 offset:55296
	ds_read_b64_tr_b16 v[138:139], v5 offset:56448
	ds_read_b64_tr_b16 v[130:131], v5 offset:56512
	ds_read_b64_tr_b16 v[128:129], v5 offset:55360
	ds_read_b64_tr_b16 v[140:141], v5 offset:57600
	ds_read_b64_tr_b16 v[142:143], v5 offset:58752
	ds_read_b64_tr_b16 v[134:135], v5 offset:58816
	ds_read_b64_tr_b16 v[132:133], v5 offset:57664
	v_lshlrev_b32_e32 v5, 1, v55
	s_add_i32 s52, s52, -1
	v_or_b32_e32 v195, 8, v5
	v_or_b32_e32 v196, 1, v5
	v_or_b32_e32 v5, 0x120, v3
	v_min_u32_e32 v5, s52, v5
	v_sub_u32_e32 v198, v5, v4
	v_or_b32_e32 v5, 32, v3
	v_max_u32_e32 v5, s51, v5
	v_sub_u32_e32 v199, v5, v4
	v_or_b32_e32 v5, 0x100, v3
	v_min_u32_e32 v5, s52, v5
	v_max_u32_e32 v3, s51, v3
	v_sub_u32_e32 v200, v5, v4
	v_sub_u32_e32 v201, v3, v4
	v_mul_u32_u24_e32 v3, 0x2400, v55
	v_mul_u32_u24_e32 v4, 0x240, v54
	v_or_b32_e32 v3, v3, v4
	v_mul_u32_u24_e32 v4, 0x90, v51
	v_add3_u32 v3, v3, v4, v6
	v_add3_u32 v202, v3, v7, 0
	v_mul_u32_u24_e32 v3, 0x90, v191
	v_cmp_eq_u32_e32 vcc, 0, v54
	v_mad_u32_u24 v3, v55, s46, v3
	v_mov_b32_e32 v14, v1
	v_mov_b32_e32 v15, v1
	v_lshlrev_b32_e32 v193, 3, v54
	v_mul_f32_e32 v205, 0x3fb8aa3b, v57
	v_cndmask_b32_e64 v192, 0, 1.0, vcc
	v_sub_u32_e32 v197, 0, v2
	v_add3_u32 v203, v3, v0, s47
	v_add_u32_e32 v204, 64, v2
	v_mov_b32_e32 v0, v1
	v_mov_b32_e32 v2, v1
	v_mov_b32_e32 v3, v1
	v_mov_b32_e32 v4, v1
	v_mov_b32_e32 v5, v1
	v_mov_b32_e32 v6, v1
	v_mov_b32_e32 v7, v1
	v_mov_b32_e32 v8, v1
	v_mov_b32_e32 v9, v1
	v_mov_b32_e32 v10, v1
	v_mov_b32_e32 v11, v1
	v_mov_b32_e32 v12, v1
	v_mov_b32_e32 v13, v1
	v_mov_b64_e32 v[30:31], v[14:15]
	v_mov_b64_e32 v[46:47], v[14:15]
	v_mov_b64_e32 v[62:63], v[14:15]
	v_mov_b64_e32 v[78:79], v[14:15]
	s_mov_b32 s18, 0
	s_nor_b64 s[28:29], s[20:21], s[26:27]
	s_mov_b32 s36, 0
	v_mov_b64_e32 v[28:29], v[12:13]
	v_mov_b64_e32 v[26:27], v[10:11]
	v_mov_b64_e32 v[24:25], v[8:9]
	v_mov_b64_e32 v[22:23], v[6:7]
	v_mov_b64_e32 v[20:21], v[4:5]
	v_mov_b64_e32 v[18:19], v[2:3]
	v_mov_b64_e32 v[16:17], v[0:1]
	v_mov_b64_e32 v[44:45], v[12:13]
	v_mov_b64_e32 v[42:43], v[10:11]
	v_mov_b64_e32 v[40:41], v[8:9]
	v_mov_b64_e32 v[38:39], v[6:7]
	v_mov_b64_e32 v[36:37], v[4:5]
	v_mov_b64_e32 v[34:35], v[2:3]
	v_mov_b64_e32 v[32:33], v[0:1]
	v_mov_b64_e32 v[60:61], v[12:13]
	v_mov_b64_e32 v[58:59], v[10:11]
	v_mov_b64_e32 v[56:57], v[8:9]
	v_mov_b64_e32 v[54:55], v[6:7]
	v_mov_b64_e32 v[52:53], v[4:5]
	v_mov_b64_e32 v[50:51], v[2:3]
	v_mov_b64_e32 v[48:49], v[0:1]
	v_mov_b64_e32 v[76:77], v[12:13]
	v_mov_b64_e32 v[74:75], v[10:11]
	v_mov_b64_e32 v[72:73], v[8:9]
	v_mov_b64_e32 v[70:71], v[6:7]
	v_mov_b64_e32 v[68:69], v[4:5]
	v_mov_b64_e32 v[66:67], v[2:3]
	v_mov_b64_e32 v[64:65], v[0:1]
	v_mov_b32_e32 v15, v205
	v_mov_b32_e32 v0, v192
